# local barriers: waiting workgroups poll the arrival counter directly (no leader round trip); release-generation compares made monotonic; otherwise as v60
# baseline (speedup 1.0000x reference)
.Lno_early_inv:
	v_cvt_f32_u32_e32 v4, v2
	s_waitcnt vmcnt(0)
	v_readfirstlane_b32 s1, v3
	v_sub_u32_e32 v3, 0, v2
	v_rcp_iflag_f32_e32 v4, v4
	v_add_u32_e32 v5, s1, v1
	v_mul_f32_e32 v4, 0x4f7ffffe, v4
	v_cvt_u32_f32_e32 v4, v4
	v_mul_lo_u32 v1, v3, v4
	v_mul_hi_u32 v1, v4, v1
	v_add_u32_e32 v1, v4, v1
	v_mul_hi_u32 v1, v5, v1
	v_mul_lo_u32 v3, v1, v2
	v_sub_u32_e32 v3, v5, v3
	v_add_u32_e32 v4, 1, v1
	v_cmp_ge_u32_e32 vcc, v3, v2
	s_nop 1
	v_cndmask_b32_e32 v1, v1, v4, vcc
	v_sub_u32_e32 v4, v3, v2
	v_cndmask_b32_e32 v3, v3, v4, vcc
	v_add_u32_e32 v4, 1, v1
	v_cmp_ge_u32_e32 vcc, v3, v2
	v_add_u32_e32 v3, 1, v5
	s_nop 0
	v_cndmask_b32_e32 v1, v1, v4, vcc
	v_mul_lo_u32 v4, v2, v1
	v_add_u32_e32 v2, v4, v2
	v_cmp_ne_u32_e32 vcc, v3, v2
	s_and_saveexec_b64 s[6:7], vcc
	s_xor_b64 s[6:7], exec, s[6:7]
	s_cbranch_execz .LBB0_95
	v_readfirstlane_b32 s1, v15
	s_cmp_eq_u32 s1, 0
	s_cbranch_scc1 .Lnl_full
	v_readlane_b32 s8, v252, 53
	v_readlane_b32 s9, v252, 54
	s_waitcnt lgkmcnt(0)
	s_nop 4
.Lnl_spin:
	global_load_dword v0, v169, s[8:9] sc1
	s_waitcnt vmcnt(0)
	v_cmp_ge_u32_e32 vcc, v0, v2
	s_cbranch_vccnz .Lnl_done
	s_sleep 1
	s_branch .Lnl_spin

.Lnl_full:
	v_readlane_b32 s8, v252, 55
	v_readlane_b32 s9, v252, 56
	s_waitcnt lgkmcnt(0)
	s_nop 3
	global_load_dword v0, v169, s[8:9] sc1
	s_waitcnt vmcnt(0)
	v_cmp_le_u32_e32 vcc, v0, v1
	s_and_saveexec_b64 s[8:9], vcc
	s_cbranch_execz .LBB0_94
	s_mov_b32 s1, 1
	s_mov_b64 s[10:11], 0
	s_branch .LBB0_85

.LBB0_87:
	v_readlane_b32 s14, v252, 55
	v_readlane_b32 s15, v252, 56
	s_add_i32 s1, s1, 1
	s_mov_b64 s[16:17], -1
	s_nop 2
	global_load_dword v0, v169, s[14:15] sc1
	s_waitcnt vmcnt(0)
	v_cmp_gt_u32_e32 vcc, v0, v1
	s_orn2_b64 s[14:15], vcc, exec
	s_branch .LBB0_84
